# S5 chunk loops: no store-ack wait in loop, 2-deep parity-alternating u prefetch, XCD-local item mapping
# baseline (speedup 1.0000x reference)
.Lro_s5:
	s_mov_b32 s10, s33
	s_mov_b32 s12, s3
	v_mov_b32_e32 v0, s75
	v_mbcnt_lo_u32_b32 v56, -1, 0
	v_mbcnt_hi_u32_b32 v56, -1, v56
	ds_read_b32 v0, v0
	s_waitcnt lgkmcnt(0)
	v_readfirstlane_b32 s11, v0
	v_mov_b32_e32 v0, s77
	ds_read_b32 v0, v0
	s_waitcnt lgkmcnt(0)
	v_mov_b32_e32 v0, s81
	ds_read_b32 v0, v0
	s_waitcnt lgkmcnt(0)
	v_readfirstlane_b32 s13, v0
	s_add_i32 s11, s11, s13
	s_mul_i32 s13, s10, 0x3200
	s_mul_i32 s45, s12, s10
	s_add_i32 s44, s13, 0
	s_add_i32 s45, s45, s11
	s_lshl_b32 s46, s12, 3
	s_cmpk_gt_i32 s12, 0x48
	s_mov_b64 s[10:11], -1
	s_cbranch_scc1 .LBB0_638
	s_cmpk_gt_i32 s45, 0x9ff
	s_cbranch_scc1 .LBB0_637
	s_load_dwordx2 s[20:21], s[0:1], 0x110
	s_load_dwordx4 s[16:19], s[0:1], 0xa8
	s_load_dwordx2 s[24:25], s[0:1], 0xb8
	s_waitcnt lgkmcnt(0)
	v_ashrrev_i32_e32 v0, 4, v56
	s_lshl_b32 s47, s58, 6
	v_lshlrev_b32_e32 v1, 3, v0
	v_and_b32_e32 v75, 15, v56
	v_mov_b32_e32 v2, s44
	s_movk_i32 s22, 0x210
	s_add_u32 s26, s20, 0xf300000
	v_and_b32_e32 v58, 8, v1
	v_bfe_u32 v59, v56, 1, 3
	v_and_b32_e32 v1, 1, v56
	v_lshlrev_b32_e32 v0, 2, v0
	v_mad_u32_u24 v3, v75, s22, v2
	s_movk_i32 s22, 0x110
	s_addc_u32 s27, s21, 0
	v_cmp_gt_i32_e64 s[10:11], 32, v56
	v_cmp_eq_u32_e64 s[14:15], 1, v1
	v_or_b32_e32 v61, 8, v59
	v_or_b32_e32 v63, 16, v59
	v_or_b32_e32 v65, 24, v59
	v_or_b32_e32 v67, 32, v59
	v_or_b32_e32 v69, 40, v59
	v_or_b32_e32 v71, 48, v59
	v_or_b32_e32 v73, 56, v59
	v_ashrrev_i32_e32 v1, 31, v0
	v_and_b32_e32 v4, -16, v56
	v_lshlrev_b32_e32 v178, 1, v58
	v_lshlrev_b32_e32 v5, 3, v56
	v_lshlrev_b32_e32 v6, 2, v56
	v_mad_u32_u24 v2, v75, s22, v2
	s_lshl_b32 s28, s58, 1
	s_mov_b32 s29, s41
	v_cmp_lt_i32_e64 s[12:13], 31, v56
	v_lshlrev_b32_e32 v60, 4, v59
	v_lshlrev_b32_e32 v62, 4, v61
	v_lshlrev_b32_e32 v64, 4, v63
	v_lshlrev_b32_e32 v66, 4, v65
	v_lshlrev_b32_e32 v68, 4, v67
	v_lshlrev_b32_e32 v70, 4, v69
	v_lshlrev_b32_e32 v72, 4, v71
	v_lshlrev_b32_e32 v74, 4, v73
	v_lshlrev_b32_e32 v76, 6, v75
	v_ashrrev_i32_e32 v57, 31, v56
	v_bitop3_b32 v77, v56, 15, v56 bitop3:0x3f
	v_lshl_add_u64 v[78:79], s[26:27], 0, v[178:179]
	v_lshl_add_u64 v[80:81], v[0:1], 2, s[20:21]
	v_lshlrev_b64 v[82:83], 2, v[0:1]
	s_xor_b64 s[30:31], s[10:11], -1
	v_add_u32_e32 v102, v3, v4
	v_add_u32_e32 v103, s44, v5
	v_add_u32_e32 v104, s44, v6
	v_add_u32_e32 v105, v2, v4
	s_mov_b32 s48, s45
	s_branch .LBB0_225

.LBB0_1042:
	s_or_b64 exec, exec, s[22:23]
	s_and_b64 s[22:23], vcc, exec
	v_mul_f32_e32 v86, v51, v50
	s_cselect_b32 s22, s4, 0x25500000
	s_mov_b32 s23, 0
	v_lshl_add_u64 v[88:89], v[48:49], 1, v[78:79]
	v_mov_b64_e32 v[48:49], v[96:97]
	s_lshr_b32 s50, s30, 4
	s_lshl_b32 s40, s47, 14
	v_lshl_add_u64 v[90:91], v[80:81], 0, s[22:23]
	v_mov_b32_e32 v87, v86
	v_mov_b32_e32 v85, v84
	v_mov_b32_e32 v92, v84
	v_mov_b32_e32 v93, v86
	v_mov_b32_e32 v94, v86
	v_mov_b32_e32 v95, v84
	v_add_u32_e32 v106, s30, v77
	v_mov_b32_e32 v107, v75
	v_mov_b64_e32 v[50:51], v[98:99]
	s_waitcnt vmcnt(0)
	v_mov_b32_e32 v156, 0
	v_mov_b32_e32 v157, 0
	v_mov_b32_e32 v158, 0
	v_mov_b32_e32 v159, 0
	v_mov_b32_e32 v160, 0
	v_mov_b32_e32 v161, 0
	v_mov_b32_e32 v162, 0
	v_mov_b32_e32 v163, 0
	v_add_u32_e32 v164, 16, v107
	v_add_u32_e32 v165, -16, v106
	v_cndmask_b32_e32 v164, v165, v164, vcc
	v_add_u32_e32 v164, s49, v164
	v_mad_i64_i32 v[164:165], s[52:53], v164, s38, v[88:89]
	s_mov_b64 s[30:31], exec
	s_andn2_b64 exec, exec, s[28:29]
	global_load_dwordx4 v[156:159], v[164:165], off
	global_load_dword v166, v[164:165], off
	s_mov_b64 exec, s[30:31]
.LBB0_1043:
	s_add_i32 s23, s23, 1
	v_add_u32_e32 v97, 16, v107
	v_add_u32_e32 v98, -16, v106
	s_add_i32 s52, s23, 2
	s_cmp_le_u32 s52, s50
	s_cselect_b32 s52, 32, 0
	v_add_u32_e32 v164, s52, v107
	v_subrev_u32_e32 v165, s52, v106
	s_nop 0
	v_cndmask_b32_e32 v164, v165, v164, vcc
	v_add_u32_e32 v164, s49, v164
	v_mad_i64_i32 v[164:165], s[52:53], v164, s38, v[88:89]
	s_mov_b64 s[30:31], exec
	s_andn2_b64 exec, exec, s[28:29]
	s_bitcmp1_b32 s23, 0
	s_cbranch_scc1 .Lpf2_ctx_odd
	global_load_dwordx4 v[156:159], v[164:165], off
	s_branch .Lpf2_ctx_join
.Lpf2_ctx_odd:
	global_load_dwordx4 v[160:163], v[164:165], off
.Lpf2_ctx_join:
	s_mov_b64 exec, s[30:31]
	v_mfma_f32_16x16x32_bf16 v[108:111], v[0:3], v[52:55], 0
	v_cndmask_b32_e32 v99, v106, v107, vcc
	v_add_u32_e32 v106, s49, v99
	v_ashrrev_i32_e32 v107, 31, v106
	v_lshl_add_u64 v[106:107], v[106:107], 0, s[40:41]
	v_lshlrev_b64 v[106:107], 6, v[106:107]
	s_nop 2
	ds_write_b128 v102, v[108:111]
	v_mfma_f32_16x16x32_bf16 v[108:111], v[4:7], v[52:55], 0
	v_lshl_add_u64 v[106:107], v[90:91], 0, v[106:107]
	s_cmp_eq_u32 s50, s23
	s_nop 5
	ds_write_b128 v102, v[108:111] offset:64
	v_mfma_f32_16x16x32_bf16 v[108:111], v[8:11], v[52:55], 0
	s_nop 7
	ds_write_b128 v102, v[108:111] offset:128
	v_mfma_f32_16x16x32_bf16 v[108:111], v[12:15], v[52:55], 0
	s_nop 7
	ds_write_b128 v102, v[108:111] offset:192
	v_mfma_f32_16x16x32_bf16 v[108:111], v[16:19], v[52:55], 0
	s_nop 7
	ds_write_b128 v102, v[108:111] offset:256
	v_mfma_f32_16x16x32_bf16 v[108:111], v[20:23], v[52:55], 0
	s_nop 7
	ds_write_b128 v102, v[108:111] offset:320
	v_mfma_f32_16x16x32_bf16 v[108:111], v[24:27], v[52:55], 0
	v_mfma_f32_16x16x32_bf16 v[52:55], v[28:31], v[52:55], 0
	s_nop 6
	ds_write_b128 v102, v[108:111] offset:384
	ds_write_b128 v102, v[52:55] offset:448
	ds_read_b64 v[120:121], v103
	ds_read_b64 v[122:123], v103 offset:528
	ds_read_b64 v[124:125], v103 offset:1056
	ds_read_b64 v[126:127], v103 offset:1584
	ds_read_b64 v[128:129], v103 offset:2112
	ds_read_b64 v[130:131], v103 offset:2640
	ds_read_b64 v[132:133], v103 offset:3168
	ds_read_b64 v[134:135], v103 offset:3696
	ds_read_b64 v[136:137], v103 offset:4224
	ds_read_b64 v[138:139], v103 offset:4752
	ds_read_b64 v[140:141], v103 offset:5280
	ds_read_b64 v[142:143], v103 offset:5808
	ds_read_b64 v[144:145], v103 offset:6336
	ds_read_b64 v[146:147], v103 offset:6864
	ds_read_b64 v[148:149], v103 offset:7392
	ds_read_b64 v[150:151], v103 offset:7920
	s_waitcnt lgkmcnt(0)
	v_mul_f32_e32 v152, v84, v101
	v_mul_f32_e32 v153, v84, v100
	v_fma_f32 v152, v86, v100, -v152
	v_fma_f32 v153, v86, v101, v153
	v_add_f32_e32 v100, v152, v120
	v_add_f32_e32 v101, v153, v121
	v_cvt_pk_bf16_f32 v154, v100, v101
	ds_write_b32 v104, v154 offset:8448
	v_mul_f32_e32 v152, v84, v101
	v_mul_f32_e32 v153, v84, v100
	v_fma_f32 v152, v86, v100, -v152
	v_fma_f32 v153, v86, v101, v153
	v_add_f32_e32 v100, v152, v122
	v_add_f32_e32 v101, v153, v123
	v_cvt_pk_bf16_f32 v155, v100, v101
	ds_write_b32 v104, v155 offset:8720
	v_mul_f32_e32 v152, v84, v101
	v_mul_f32_e32 v153, v84, v100
	v_fma_f32 v152, v86, v100, -v152
	v_fma_f32 v153, v86, v101, v153
	v_add_f32_e32 v100, v152, v124
	v_add_f32_e32 v101, v153, v125
	v_cvt_pk_bf16_f32 v154, v100, v101
	ds_write_b32 v104, v154 offset:8992
	v_mul_f32_e32 v152, v84, v101
	v_mul_f32_e32 v153, v84, v100
	v_fma_f32 v152, v86, v100, -v152
	v_fma_f32 v153, v86, v101, v153
	v_add_f32_e32 v100, v152, v126
	v_add_f32_e32 v101, v153, v127
	v_cvt_pk_bf16_f32 v155, v100, v101
	ds_write_b32 v104, v155 offset:9264
	v_mul_f32_e32 v152, v84, v101
	v_mul_f32_e32 v153, v84, v100
	v_fma_f32 v152, v86, v100, -v152
	v_fma_f32 v153, v86, v101, v153
	v_add_f32_e32 v100, v152, v128
	v_add_f32_e32 v101, v153, v129
	v_cvt_pk_bf16_f32 v154, v100, v101
	ds_write_b32 v104, v154 offset:9536
	v_mul_f32_e32 v152, v84, v101
	v_mul_f32_e32 v153, v84, v100
	v_fma_f32 v152, v86, v100, -v152
	v_fma_f32 v153, v86, v101, v153
	v_add_f32_e32 v100, v152, v130
	v_add_f32_e32 v101, v153, v131
	v_cvt_pk_bf16_f32 v155, v100, v101
	ds_write_b32 v104, v155 offset:9808
	v_mul_f32_e32 v152, v84, v101
	v_mul_f32_e32 v153, v84, v100
	v_fma_f32 v152, v86, v100, -v152
	v_fma_f32 v153, v86, v101, v153
	v_add_f32_e32 v100, v152, v132
	v_add_f32_e32 v101, v153, v133
	v_cvt_pk_bf16_f32 v154, v100, v101
	ds_write_b32 v104, v154 offset:10080
	v_mul_f32_e32 v152, v84, v101
	v_mul_f32_e32 v153, v84, v100
	v_fma_f32 v152, v86, v100, -v152
	v_fma_f32 v153, v86, v101, v153
	v_add_f32_e32 v100, v152, v134
	v_add_f32_e32 v101, v153, v135
	v_cvt_pk_bf16_f32 v155, v100, v101
	ds_write_b32 v104, v155 offset:10352
	v_mul_f32_e32 v152, v84, v101
	v_mul_f32_e32 v153, v84, v100
	v_fma_f32 v152, v86, v100, -v152
	v_fma_f32 v153, v86, v101, v153
	v_add_f32_e32 v100, v152, v136
	v_add_f32_e32 v101, v153, v137
	v_cvt_pk_bf16_f32 v154, v100, v101
	ds_write_b32 v104, v154 offset:10624
	v_mul_f32_e32 v152, v84, v101
	v_mul_f32_e32 v153, v84, v100
	v_fma_f32 v152, v86, v100, -v152
	v_fma_f32 v153, v86, v101, v153
	v_add_f32_e32 v100, v152, v138
	v_add_f32_e32 v101, v153, v139
	v_cvt_pk_bf16_f32 v155, v100, v101
	ds_write_b32 v104, v155 offset:10896
	v_mul_f32_e32 v152, v84, v101
	v_mul_f32_e32 v153, v84, v100
	v_fma_f32 v152, v86, v100, -v152
	v_fma_f32 v153, v86, v101, v153
	v_add_f32_e32 v100, v152, v140
	v_add_f32_e32 v101, v153, v141
	v_cvt_pk_bf16_f32 v154, v100, v101
	ds_write_b32 v104, v154 offset:11168
	v_mul_f32_e32 v152, v84, v101
	v_mul_f32_e32 v153, v84, v100
	v_fma_f32 v152, v86, v100, -v152
	v_fma_f32 v153, v86, v101, v153
	v_add_f32_e32 v100, v152, v142
	v_add_f32_e32 v101, v153, v143
	v_cvt_pk_bf16_f32 v155, v100, v101
	ds_write_b32 v104, v155 offset:11440
	v_mul_f32_e32 v152, v84, v101
	v_mul_f32_e32 v153, v84, v100
	v_fma_f32 v152, v86, v100, -v152
	v_fma_f32 v153, v86, v101, v153
	v_add_f32_e32 v100, v152, v144
	v_add_f32_e32 v101, v153, v145
	v_cvt_pk_bf16_f32 v154, v100, v101
	ds_write_b32 v104, v154 offset:11712
	v_mul_f32_e32 v152, v84, v101
	v_mul_f32_e32 v153, v84, v100
	v_fma_f32 v152, v86, v100, -v152
	v_fma_f32 v153, v86, v101, v153
	v_add_f32_e32 v100, v152, v146
	v_add_f32_e32 v101, v153, v147
	v_cvt_pk_bf16_f32 v155, v100, v101
	ds_write_b32 v104, v155 offset:11984
	v_mul_f32_e32 v152, v84, v101
	v_mul_f32_e32 v153, v84, v100
	v_fma_f32 v152, v86, v100, -v152
	v_fma_f32 v153, v86, v101, v153
	v_add_f32_e32 v100, v152, v148
	v_add_f32_e32 v101, v153, v149
	v_cvt_pk_bf16_f32 v154, v100, v101
	ds_write_b32 v104, v154 offset:12256
	v_mul_f32_e32 v152, v84, v101
	v_mul_f32_e32 v153, v84, v100
	v_fma_f32 v152, v86, v100, -v152
	v_fma_f32 v153, v86, v101, v153
	v_add_f32_e32 v100, v152, v150
	v_add_f32_e32 v101, v153, v151
	v_cvt_pk_bf16_f32 v155, v100, v101
	ds_write_b32 v104, v155 offset:12528
	ds_read_b128 v[120:123], v105 offset:8448
	ds_read_b128 v[124:127], v105 offset:8512
	ds_read_b128 v[128:131], v105 offset:8576
	ds_read_b128 v[132:135], v105 offset:8640
	s_waitcnt lgkmcnt(3)
	v_mfma_f32_16x16x32_bf16 v[52:55], v[32:35], v[120:123], 0
	s_waitcnt lgkmcnt(2)
	v_mfma_f32_16x16x32_bf16 v[52:55], v[36:39], v[124:127], v[52:55]
	s_waitcnt lgkmcnt(1)
	v_mfma_f32_16x16x32_bf16 v[52:55], v[40:43], v[128:131], v[52:55]
	s_waitcnt lgkmcnt(0)
	v_mfma_f32_16x16x32_bf16 v[52:55], v[44:47], v[132:135], v[52:55]
	s_nop 7
	global_store_dwordx4 v[106:107], v[52:55], off
	s_cbranch_scc1 .LBB0_1049
	s_nop 0
	s_waitcnt vmcnt(3)
	s_bitcmp1_b32 s23, 0
	s_cbranch_scc1 .Lcp2_ctx_a
	v_mov_b64_e32 v[52:53], v[160:161]
	v_mov_b64_e32 v[54:55], v[162:163]
	s_branch .Lcp2_ctx_done
.Lcp2_ctx_a:
	v_mov_b64_e32 v[52:53], v[156:157]
	v_mov_b64_e32 v[54:55], v[158:159]
.Lcp2_ctx_done:
	v_mov_b32_e32 v106, v98
	v_mov_b32_e32 v107, v97
	s_branch .LBB0_1043

.LBB0_1452:
	s_or_b64 exec, exec, s[12:13]
	s_and_b64 s[12:13], vcc, exec
	s_cselect_b32 s12, s4, 0x25500000
	s_add_u32 s12, s14, s12
	s_addc_u32 s13, s15, 0
	v_mov_b32_e32 v59, s44
	s_movk_i32 s15, 0x210
	v_lshl_add_u64 v[50:51], v[50:51], 1, s[20:21]
	v_mad_u32_u24 v74, v72, s15, v59
	v_lshl_add_u64 v[64:65], v[50:51], 0, v[178:179]
	v_lshlrev_b32_e32 v50, 3, v56
	v_lshlrev_b32_e32 v51, 2, v56
	s_movk_i32 s15, 0x110
	v_mul_f32_e32 v60, v61, v60
	v_and_b32_e32 v77, -16, v56
	v_mad_u32_u24 v78, v72, s15, v59
	v_lshl_add_u64 v[66:67], v[48:49], 2, s[12:13]
	v_add_u32_e32 v75, s44, v50
	v_add_u32_e32 v76, s44, v51
	v_mov_b64_e32 v[48:49], v[96:97]
	s_mov_b32 s23, 0
	s_lshr_b32 s14, s25, 4
	s_lshl_b32 s40, s22, 14
	v_mov_b32_e32 v61, v60
	v_mov_b32_e32 v59, v58
	v_mov_b32_e32 v68, v58
	v_mov_b32_e32 v69, v60
	v_mov_b32_e32 v70, v60
	v_mov_b32_e32 v71, v58
	s_xor_b64 s[10:11], s[10:11], -1
	v_add_u32_e32 v74, v74, v77
	v_add_u32_e32 v77, v78, v77
	v_mov_b64_e32 v[50:51], v[98:99]
	s_waitcnt vmcnt(0)
	v_mov_b32_e32 v156, 0
	v_mov_b32_e32 v157, 0
	v_mov_b32_e32 v158, 0
	v_mov_b32_e32 v159, 0
	v_mov_b32_e32 v160, 0
	v_mov_b32_e32 v161, 0
	v_mov_b32_e32 v162, 0
	v_mov_b32_e32 v163, 0
	v_add_u32_e32 v164, 16, v72
	v_add_u32_e32 v165, -16, v73
	v_cndmask_b32_e32 v164, v165, v164, vcc
	v_add_u32_e32 v164, s17, v164
	v_mad_i64_i32 v[164:165], s[20:21], v164, s38, v[64:65]
	s_mov_b64 s[12:13], exec
	s_andn2_b64 exec, exec, s[10:11]
	global_load_dwordx4 v[156:159], v[164:165], off
	global_load_dword v166, v[164:165], off
	s_mov_b64 exec, s[12:13]
.LBB0_1453:
	s_add_i32 s23, s23, 1
	v_add_u32_e32 v78, 16, v72
	v_add_u32_e32 v79, -16, v73
	s_add_i32 s20, s23, 2
	s_cmp_le_u32 s20, s14
	s_cselect_b32 s20, 32, 0
	v_add_u32_e32 v164, s20, v72
	v_subrev_u32_e32 v165, s20, v73
	s_nop 0
	v_cndmask_b32_e32 v164, v165, v164, vcc
	v_add_u32_e32 v164, s17, v164
	v_mad_i64_i32 v[164:165], s[20:21], v164, s38, v[64:65]
	s_mov_b64 s[12:13], exec
	s_andn2_b64 exec, exec, s[10:11]
	s_bitcmp1_b32 s23, 0
	s_cbranch_scc1 .Lpf2_lat_odd
	global_load_dwordx4 v[156:159], v[164:165], off
	s_branch .Lpf2_lat_join

.Lpf2_lat_join:
	s_mov_b64 exec, s[12:13]
	v_mfma_f32_16x16x32_bf16 v[80:83], v[0:3], v[52:55], 0
	v_cndmask_b32_e32 v72, v73, v72, vcc
	v_add_u32_e32 v72, s17, v72
	v_ashrrev_i32_e32 v73, 31, v72
	v_lshl_add_u64 v[72:73], v[72:73], 0, s[40:41]
	v_lshlrev_b64 v[72:73], 6, v[72:73]
	s_nop 2
	ds_write_b128 v74, v[80:83]
	v_mfma_f32_16x16x32_bf16 v[80:83], v[4:7], v[52:55], 0
	v_lshl_add_u64 v[72:73], v[66:67], 0, v[72:73]
	s_cmp_eq_u32 s14, s23
	s_nop 5
	ds_write_b128 v74, v[80:83] offset:64
	v_mfma_f32_16x16x32_bf16 v[80:83], v[8:11], v[52:55], 0
	s_nop 7
	ds_write_b128 v74, v[80:83] offset:128
	v_mfma_f32_16x16x32_bf16 v[80:83], v[12:15], v[52:55], 0
	s_nop 7
	ds_write_b128 v74, v[80:83] offset:192
	v_mfma_f32_16x16x32_bf16 v[80:83], v[16:19], v[52:55], 0
	s_nop 7
	ds_write_b128 v74, v[80:83] offset:256
	v_mfma_f32_16x16x32_bf16 v[80:83], v[20:23], v[52:55], 0
	s_nop 7
	ds_write_b128 v74, v[80:83] offset:320
	v_mfma_f32_16x16x32_bf16 v[80:83], v[24:27], v[52:55], 0
	v_mfma_f32_16x16x32_bf16 v[52:55], v[28:31], v[52:55], 0
	s_nop 6
	ds_write_b128 v74, v[80:83] offset:384
	ds_write_b128 v74, v[52:55] offset:448
	ds_read_b64 v[120:121], v75
	ds_read_b64 v[122:123], v75 offset:528
	ds_read_b64 v[124:125], v75 offset:1056
	ds_read_b64 v[126:127], v75 offset:1584
	ds_read_b64 v[128:129], v75 offset:2112
	ds_read_b64 v[130:131], v75 offset:2640
	ds_read_b64 v[132:133], v75 offset:3168
	ds_read_b64 v[134:135], v75 offset:3696
	ds_read_b64 v[136:137], v75 offset:4224
	ds_read_b64 v[138:139], v75 offset:4752
	ds_read_b64 v[140:141], v75 offset:5280
	ds_read_b64 v[142:143], v75 offset:5808
	ds_read_b64 v[144:145], v75 offset:6336
	ds_read_b64 v[146:147], v75 offset:6864
	ds_read_b64 v[148:149], v75 offset:7392
	ds_read_b64 v[150:151], v75 offset:7920
	s_waitcnt lgkmcnt(0)
	v_mul_f32_e32 v152, v58, v63
	v_mul_f32_e32 v153, v58, v62
	v_fma_f32 v152, v60, v62, -v152
	v_fma_f32 v153, v60, v63, v153
	v_add_f32_e32 v62, v152, v120
	v_add_f32_e32 v63, v153, v121
	v_cvt_pk_bf16_f32 v154, v62, v63
	ds_write_b32 v76, v154 offset:8448
	v_mul_f32_e32 v152, v58, v63
	v_mul_f32_e32 v153, v58, v62
	v_fma_f32 v152, v60, v62, -v152
	v_fma_f32 v153, v60, v63, v153
	v_add_f32_e32 v62, v152, v122
	v_add_f32_e32 v63, v153, v123
	v_cvt_pk_bf16_f32 v155, v62, v63
	ds_write_b32 v76, v155 offset:8720
	v_mul_f32_e32 v152, v58, v63
	v_mul_f32_e32 v153, v58, v62
	v_fma_f32 v152, v60, v62, -v152
	v_fma_f32 v153, v60, v63, v153
	v_add_f32_e32 v62, v152, v124
	v_add_f32_e32 v63, v153, v125
	v_cvt_pk_bf16_f32 v154, v62, v63
	ds_write_b32 v76, v154 offset:8992
	v_mul_f32_e32 v152, v58, v63
	v_mul_f32_e32 v153, v58, v62
	v_fma_f32 v152, v60, v62, -v152
	v_fma_f32 v153, v60, v63, v153
	v_add_f32_e32 v62, v152, v126
	v_add_f32_e32 v63, v153, v127
	v_cvt_pk_bf16_f32 v155, v62, v63
	ds_write_b32 v76, v155 offset:9264
	v_mul_f32_e32 v152, v58, v63
	v_mul_f32_e32 v153, v58, v62
	v_fma_f32 v152, v60, v62, -v152
	v_fma_f32 v153, v60, v63, v153
	v_add_f32_e32 v62, v152, v128
	v_add_f32_e32 v63, v153, v129
	v_cvt_pk_bf16_f32 v154, v62, v63
	ds_write_b32 v76, v154 offset:9536
	v_mul_f32_e32 v152, v58, v63
	v_mul_f32_e32 v153, v58, v62
	v_fma_f32 v152, v60, v62, -v152
	v_fma_f32 v153, v60, v63, v153
	v_add_f32_e32 v62, v152, v130
	v_add_f32_e32 v63, v153, v131
	v_cvt_pk_bf16_f32 v155, v62, v63
	ds_write_b32 v76, v155 offset:9808
	v_mul_f32_e32 v152, v58, v63
	v_mul_f32_e32 v153, v58, v62
	v_fma_f32 v152, v60, v62, -v152
	v_fma_f32 v153, v60, v63, v153
	v_add_f32_e32 v62, v152, v132
	v_add_f32_e32 v63, v153, v133
	v_cvt_pk_bf16_f32 v154, v62, v63
	ds_write_b32 v76, v154 offset:10080
	v_mul_f32_e32 v152, v58, v63
	v_mul_f32_e32 v153, v58, v62
	v_fma_f32 v152, v60, v62, -v152
	v_fma_f32 v153, v60, v63, v153
	v_add_f32_e32 v62, v152, v134
	v_add_f32_e32 v63, v153, v135
	v_cvt_pk_bf16_f32 v155, v62, v63
	ds_write_b32 v76, v155 offset:10352
	v_mul_f32_e32 v152, v58, v63
	v_mul_f32_e32 v153, v58, v62
	v_fma_f32 v152, v60, v62, -v152
	v_fma_f32 v153, v60, v63, v153
	v_add_f32_e32 v62, v152, v136
	v_add_f32_e32 v63, v153, v137
	v_cvt_pk_bf16_f32 v154, v62, v63
	ds_write_b32 v76, v154 offset:10624
	v_mul_f32_e32 v152, v58, v63
	v_mul_f32_e32 v153, v58, v62
	v_fma_f32 v152, v60, v62, -v152
	v_fma_f32 v153, v60, v63, v153
	v_add_f32_e32 v62, v152, v138
	v_add_f32_e32 v63, v153, v139
	v_cvt_pk_bf16_f32 v155, v62, v63
	ds_write_b32 v76, v155 offset:10896
	v_mul_f32_e32 v152, v58, v63
	v_mul_f32_e32 v153, v58, v62
	v_fma_f32 v152, v60, v62, -v152
	v_fma_f32 v153, v60, v63, v153
	v_add_f32_e32 v62, v152, v140
	v_add_f32_e32 v63, v153, v141
	v_cvt_pk_bf16_f32 v154, v62, v63
	ds_write_b32 v76, v154 offset:11168
	v_mul_f32_e32 v152, v58, v63
	v_mul_f32_e32 v153, v58, v62
	v_fma_f32 v152, v60, v62, -v152
	v_fma_f32 v153, v60, v63, v153
	v_add_f32_e32 v62, v152, v142
	v_add_f32_e32 v63, v153, v143
	v_cvt_pk_bf16_f32 v155, v62, v63
	ds_write_b32 v76, v155 offset:11440
	v_mul_f32_e32 v152, v58, v63
	v_mul_f32_e32 v153, v58, v62
	v_fma_f32 v152, v60, v62, -v152
	v_fma_f32 v153, v60, v63, v153
	v_add_f32_e32 v62, v152, v144
	v_add_f32_e32 v63, v153, v145
	v_cvt_pk_bf16_f32 v154, v62, v63
	ds_write_b32 v76, v154 offset:11712
	v_mul_f32_e32 v152, v58, v63
	v_mul_f32_e32 v153, v58, v62
	v_fma_f32 v152, v60, v62, -v152
	v_fma_f32 v153, v60, v63, v153
	v_add_f32_e32 v62, v152, v146
	v_add_f32_e32 v63, v153, v147
	v_cvt_pk_bf16_f32 v155, v62, v63
	ds_write_b32 v76, v155 offset:11984
	v_mul_f32_e32 v152, v58, v63
	v_mul_f32_e32 v153, v58, v62
	v_fma_f32 v152, v60, v62, -v152
	v_fma_f32 v153, v60, v63, v153
	v_add_f32_e32 v62, v152, v148
	v_add_f32_e32 v63, v153, v149
	v_cvt_pk_bf16_f32 v154, v62, v63
	ds_write_b32 v76, v154 offset:12256
	v_mul_f32_e32 v152, v58, v63
	v_mul_f32_e32 v153, v58, v62
	v_fma_f32 v152, v60, v62, -v152
	v_fma_f32 v153, v60, v63, v153
	v_add_f32_e32 v62, v152, v150
	v_add_f32_e32 v63, v153, v151
	v_cvt_pk_bf16_f32 v155, v62, v63
	ds_write_b32 v76, v155 offset:12528
	ds_read_b128 v[120:123], v77 offset:8448
	ds_read_b128 v[124:127], v77 offset:8512
	ds_read_b128 v[128:131], v77 offset:8576
	ds_read_b128 v[132:135], v77 offset:8640
	s_waitcnt lgkmcnt(3)
	v_mfma_f32_16x16x32_bf16 v[52:55], v[32:35], v[120:123], 0
	s_waitcnt lgkmcnt(2)
	v_mfma_f32_16x16x32_bf16 v[52:55], v[36:39], v[124:127], v[52:55]
	s_waitcnt lgkmcnt(1)
	v_mfma_f32_16x16x32_bf16 v[52:55], v[40:43], v[128:131], v[52:55]
	s_waitcnt lgkmcnt(0)
	v_mfma_f32_16x16x32_bf16 v[52:55], v[44:47], v[132:135], v[52:55]
	s_nop 7
	global_store_dwordx4 v[72:73], v[52:55], off
	s_cbranch_scc1 .LBB0_1459
	s_nop 0
	s_waitcnt vmcnt(3)
	s_bitcmp1_b32 s23, 0
	s_cbranch_scc1 .Lcp2_lat_a
	v_mov_b64_e32 v[52:53], v[160:161]
	v_mov_b64_e32 v[54:55], v[162:163]
	s_branch .Lcp2_lat_done

.Lcp2_lat_done:
	v_mov_b32_e32 v73, v79
	v_mov_b32_e32 v72, v78
	s_branch .LBB0_1453
